# rwkv scan producer: d16_hi chunk loads (registers hold the f32 of the bf16 directly), LDS write block without the 48 shift instructions
# baseline (speedup 1.0000x reference)
; __device__ __forceinline__ void rwkv_load_chunk(RwkvRegs& R, int n, int pw, int b, int col, const bf16_t* RKV, const bf16_t* LO, const bf16_t* Y) {
; #pragma unroll
;     for (int i = 0; i < 8; ++i) { const int tt = pw + 4 * i, m = b * T_ + 32 * n + tt; const bf16_t* zr = RKV + (size_t)m * RKV_LD; const bf16_t* lo = LO + (size_t)m * 2048;
;         R.vr[i] = zr[col]; R.vx[i] = zr[512 + col]; R.vv[i] = zr[1024 + col]; R.ve[i] = lo[col]; R.va[i] = lo[512 + col]; R.vk[i] = Y[(size_t)m * D_ + col]; }
; __device__ __forceinline__ void rwkv_scan(const Ctx& c, const Params& p, int o, int nblk) {
;     ...
;             rwkv_load_chunk(R, 0, pw, b, col, RKV, LO, Y); rwkv_write_chunk(L, R, 0, pw, c.lane);
.LBB0_96:
	s_and_b64 vcc, exec, s[2:3]
	s_cbranch_vccz .LBB0_89
	s_and_b32 s2, s48, 0xffffe000
	v_readlane_b32 s0, v255, 46
	s_add_i32 s59, s0, s2
	s_lshl_b32 s2, s49, 4
	s_lshl_b32 s58, s49, 8
	s_and_b32 s2, s2, 0x1c0
	s_and_b32 s36, s58, 0xffffe000
	v_add_u32_e32 v2, s2, v164
	s_add_i32 s2, s36, s20
	s_ashr_i32 s3, s2, 31
	s_mul_i32 s39, s2, 0xc00
	s_mul_hi_i32 s11, s2, 0xc00
	s_add_u32 s10, s16, s39
	s_addc_u32 s11, s17, s11
	s_lshl_b64 s[18:19], s[2:3], 12
	v_ashrrev_i32_e32 v3, 31, v2
	s_add_u32 s18, s12, s18
	v_lshlrev_b64 v[2:3], 1, v[2:3]
	s_addc_u32 s19, s13, s19
	s_waitcnt vmcnt(0) lgkmcnt(0)
	v_lshl_add_u64 v[48:49], s[18:19], 0, v[2:3]
	s_add_i32 s18, s36, s0
	v_lshl_add_u64 v[4:5], s[74:75], 0, v[2:3]
	v_lshl_add_u64 v[46:47], s[10:11], 0, v[2:3]
	s_lshl_b64 s[10:11], s[2:3], 11
	s_ashr_i32 s19, s18, 31
	s_mul_i32 s3, s18, 0xc00
	v_lshl_add_u64 v[50:51], v[4:5], 0, s[10:11]
	s_mul_hi_i32 s11, s18, 0xc00
	s_add_u32 s10, s16, s3
	s_addc_u32 s11, s17, s11
	s_lshl_b64 s[62:63], s[18:19], 12
	s_add_u32 s62, s12, s62
	s_addc_u32 s63, s13, s63
	v_lshl_add_u64 v[36:37], s[10:11], 0, v[2:3]
	s_lshl_b64 s[10:11], s[18:19], 11
	global_load_ushort v59, v[46:47], off
	v_lshl_add_u64 v[52:53], v[4:5], 0, s[10:11]
	s_add_i32 s10, s2, 8
	s_ashr_i32 s11, s10, 31
	s_add_i32 s36, s39, 0x6000
	v_lshl_add_u64 v[42:43], s[62:63], 0, v[2:3]
	s_mul_hi_i32 s19, s10, 0xc00
	s_add_u32 s62, s16, s36
	s_addc_u32 s63, s17, s19
	s_lshl_b64 s[72:73], s[10:11], 12
	s_add_u32 s72, s12, s72
	s_addc_u32 s73, s13, s73
	s_lshl_b64 s[10:11], s[10:11], 11
	v_lshl_add_u64 v[44:45], v[4:5], 0, s[10:11]
	s_add_i32 s10, s2, 12
	s_ashr_i32 s11, s10, 31
	s_add_i32 s36, s39, 0x9000
	v_lshl_add_u64 v[32:33], s[62:63], 0, v[2:3]
	s_mul_hi_i32 s19, s10, 0xc00
	s_add_u32 s62, s16, s36
	v_lshl_add_u64 v[40:41], s[72:73], 0, v[2:3]
	s_addc_u32 s63, s17, s19
	s_lshl_b64 s[72:73], s[10:11], 12
	s_add_u32 s72, s12, s72
	s_addc_u32 s73, s13, s73
	s_lshl_b64 s[10:11], s[10:11], 11
	v_lshl_add_u64 v[38:39], v[4:5], 0, s[10:11]
	s_add_i32 s10, s2, 16
	s_ashr_i32 s11, s10, 31
	s_add_i32 s36, s39, 0xc000
	v_lshl_add_u64 v[26:27], s[62:63], 0, v[2:3]
	s_mul_hi_i32 s19, s10, 0xc00
	s_add_u32 s62, s16, s36
	v_lshl_add_u64 v[34:35], s[72:73], 0, v[2:3]
	s_addc_u32 s63, s17, s19
	s_lshl_b64 s[72:73], s[10:11], 12
	s_add_u32 s72, s12, s72
	s_addc_u32 s73, s13, s73
	s_lshl_b64 s[10:11], s[10:11], 11
	v_lshl_add_u64 v[30:31], v[4:5], 0, s[10:11]
	s_add_i32 s10, s2, 20
	s_ashr_i32 s11, s10, 31
	s_add_i32 s36, s39, 0xf000
	v_lshl_add_u64 v[20:21], s[62:63], 0, v[2:3]
	s_mul_hi_i32 s19, s10, 0xc00
	s_add_u32 s62, s16, s36
	v_lshl_add_u64 v[28:29], s[72:73], 0, v[2:3]
	s_addc_u32 s63, s17, s19
	s_lshl_b64 s[72:73], s[10:11], 12
	s_add_u32 s72, s12, s72
	s_addc_u32 s73, s13, s73
	s_lshl_b64 s[10:11], s[10:11], 11
	v_lshl_add_u64 v[24:25], v[4:5], 0, s[10:11]
	s_add_i32 s10, s2, 24
	s_ashr_i32 s11, s10, 31
	s_add_i32 s36, s39, 0x12000
	v_lshl_add_u64 v[14:15], s[62:63], 0, v[2:3]
	s_mul_hi_i32 s19, s10, 0xc00
	s_add_u32 s62, s16, s36
	v_lshl_add_u64 v[22:23], s[72:73], 0, v[2:3]
	s_addc_u32 s63, s17, s19
	s_lshl_b64 s[72:73], s[10:11], 12
	s_add_u32 s72, s12, s72
	s_addc_u32 s73, s13, s73
	s_lshl_b64 s[10:11], s[10:11], 11
	v_lshl_add_u64 v[18:19], v[4:5], 0, s[10:11]
	s_add_i32 s10, s2, 28
	s_ashr_i32 s11, s10, 31
	s_add_i32 s39, s39, 0x15000
	v_lshl_add_u64 v[8:9], s[62:63], 0, v[2:3]
	s_mul_hi_i32 s2, s10, 0xc00
	s_add_u32 s62, s16, s39
	v_lshl_add_u64 v[16:17], s[72:73], 0, v[2:3]
	s_addc_u32 s63, s17, s2
	s_lshl_b64 s[72:73], s[10:11], 12
	s_add_u32 s72, s12, s72
	s_addc_u32 s73, s13, s73
	s_lshl_b64 s[10:11], s[10:11], 11
	v_lshl_add_u64 v[6:7], s[62:63], 0, v[2:3]
	v_lshl_add_u64 v[10:11], s[72:73], 0, v[2:3]
	v_lshl_add_u64 v[12:13], v[4:5], 0, s[10:11]
	global_load_ushort v60, v[48:49], off
	global_load_ushort v61, v[46:47], off offset:1024
	s_nop 0
	global_load_ushort v50, v[50:51], off
	s_nop 0
	global_load_ushort v48, v[48:49], off offset:1024
	s_nop 0
	global_load_ushort v46, v[46:47], off offset:2048
	s_nop 0
	global_load_ushort v47, v[36:37], off
	global_load_ushort v49, v[42:43], off
	global_load_ushort v51, v[36:37], off offset:1024
	s_nop 0
	global_load_ushort v52, v[52:53], off
	s_nop 0
	global_load_ushort v42, v[42:43], off offset:1024
	s_nop 0
	global_load_ushort v36, v[36:37], off offset:2048
	s_nop 0
	global_load_ushort v37, v[32:33], off
	global_load_ushort v43, v[40:41], off
	global_load_ushort v53, v[32:33], off offset:1024
	s_nop 0
	global_load_ushort v44, v[44:45], off
	s_nop 0
	global_load_ushort v40, v[40:41], off offset:1024
	s_nop 0
	global_load_ushort v32, v[32:33], off offset:2048
	s_nop 0
	global_load_ushort v33, v[26:27], off
	global_load_ushort v41, v[34:35], off
	global_load_ushort v45, v[26:27], off offset:1024
	s_nop 0
	global_load_ushort v38, v[38:39], off
	s_nop 0
	global_load_ushort v34, v[34:35], off offset:1024
	s_nop 0
	global_load_ushort v26, v[26:27], off offset:2048
	s_nop 0
	global_load_ushort v27, v[20:21], off
	global_load_ushort v35, v[28:29], off
	global_load_ushort v39, v[20:21], off offset:1024
	s_nop 0
	global_load_ushort v30, v[30:31], off
	s_nop 0
	global_load_ushort v28, v[28:29], off offset:1024
	s_nop 0
	global_load_ushort v20, v[20:21], off offset:2048
	s_nop 0
	global_load_ushort v21, v[14:15], off
	global_load_ushort v29, v[22:23], off
	global_load_ushort v31, v[14:15], off offset:1024
	s_nop 0
	global_load_ushort v24, v[24:25], off
	s_nop 0
	global_load_ushort v22, v[22:23], off offset:1024
	s_nop 0
	global_load_ushort v14, v[14:15], off offset:2048
	s_nop 0
	global_load_ushort v15, v[8:9], off
	global_load_ushort v23, v[16:17], off
	global_load_ushort v25, v[8:9], off offset:1024
	s_nop 0
	global_load_ushort v18, v[18:19], off
	s_nop 0
	global_load_ushort v16, v[16:17], off offset:1024
	s_nop 0
	global_load_ushort v8, v[8:9], off offset:2048
	s_nop 0
	global_load_ushort v9, v[6:7], off
	global_load_ushort v17, v[10:11], off
	global_load_ushort v19, v[6:7], off offset:1024
	s_nop 0
	global_load_ushort v12, v[12:13], off
	s_nop 0
	global_load_ushort v10, v[10:11], off offset:1024
	s_nop 0
	global_load_ushort v6, v[6:7], off offset:2048
	s_waitcnt vmcnt(0) lgkmcnt(0)
; #define LAS __attribute__((address_space(3)))
; __device__ __forceinline__ float bf2f(bf16_t b) { return asf((unsigned)b << 16); }
; __device__ __forceinline__ void rwkv_write_chunk(LAS float* L, const RwkvRegs& R, int n, int pw, int lane) {
;     LAS float* st = L + (n & 1) * 12288;
; #pragma unroll
;     for (int i = 0; i < 8; ++i) { const int tt = pw + 4 * i; LAS float* q = st + tt * 64 + lane;
;         q[0] = bf2f(R.vr[i]); q[2048] = __expf(-bf2f(R.ve[i])); q[4096] = bf2f(R.vx[i]); q[6144] = bf2f(R.vk[i]); q[8192] = bf2f(R.va[i]); q[10240] = bf2f(R.vv[i]); }
; }
; __device__ __forceinline__ void rwkv_scan(const Ctx& c, const Params& p, int o, int nblk) {
;     ...
;             rwkv_load_chunk(R, 0, pw, b, col, RKV, LO, Y); rwkv_write_chunk(L, R, 0, pw, c.lane);
;             rwkv_load_chunk(R, 1, pw, b, col, RKV, LO, Y);
	v_lshlrev_b32_e32 v59, 16, v59
	s_add_i32 s10, s18, 28
	s_ashr_i32 s11, s10, 31
	s_add_i32 s19, s3, 0x15000
	s_mul_hi_i32 s2, s10, 0xc00
	s_add_u32 s62, s16, s19
	s_addc_u32 s63, s17, s2
	s_lshl_b64 s[72:73], s[10:11], 12
	s_add_u32 s72, s12, s72
	s_addc_u32 s73, s13, s73
	s_lshl_b64 s[10:11], s[10:11], 11
	s_add_i32 s19, s3, 0x18000
	s_movk_i32 s46, 0xf800
	v_lshlrev_b32_e32 v7, 16, v60
	v_mul_f32_e32 v7, 0xbfb8aa3b, v7
	v_exp_f32_e32 v7, v7
	v_lshlrev_b32_e32 v11, 16, v61
	v_lshlrev_b32_e32 v13, 16, v50
	v_lshlrev_b32_e32 v47, 16, v47
	ds_write2st64_b32 v56, v59, v47 offset1:4
	v_lshlrev_b32_e32 v47, 16, v49
	v_mul_f32_e32 v47, 0xbfb8aa3b, v47
	v_exp_f32_e32 v47, v47
	v_lshlrev_b32_e32 v48, 16, v48
	v_lshlrev_b32_e32 v46, 16, v46
	ds_write2st64_b32 v56, v7, v47 offset0:32 offset1:36
	v_lshlrev_b32_e32 v7, 16, v51
	ds_write2st64_b32 v56, v11, v7 offset0:64 offset1:68
	v_lshlrev_b32_e32 v7, 16, v52
	ds_write2st64_b32 v56, v13, v7 offset0:96 offset1:100
	v_lshlrev_b32_e32 v7, 16, v42
	ds_write2st64_b32 v56, v48, v7 offset0:128 offset1:132
	v_lshlrev_b32_e32 v7, 16, v36
	ds_write2st64_b32 v56, v46, v7 offset0:160 offset1:164
	v_lshlrev_b32_e32 v7, 16, v37
	v_lshlrev_b32_e32 v33, 16, v33
	v_lshlrev_b32_e32 v11, 16, v43
	ds_write2st64_b32 v56, v7, v33 offset0:8 offset1:12
	v_lshlrev_b32_e32 v7, 16, v41
	v_mul_f32_e32 v11, 0xbfb8aa3b, v11
	v_mul_f32_e32 v7, 0xbfb8aa3b, v7
	v_exp_f32_e32 v11, v11
	v_exp_f32_e32 v7, v7
	v_lshlrev_b32_e32 v13, 16, v53
	v_lshlrev_b32_e32 v36, 16, v44
	v_lshlrev_b32_e32 v37, 16, v40
	ds_write2st64_b32 v56, v11, v7 offset0:40 offset1:44
	v_lshlrev_b32_e32 v7, 16, v45
	ds_write2st64_b32 v56, v13, v7 offset0:72 offset1:76
	v_lshlrev_b32_e32 v7, 16, v38
	ds_write2st64_b32 v56, v36, v7 offset0:104 offset1:108
	v_lshlrev_b32_e32 v7, 16, v34
	v_lshlrev_b32_e32 v32, 16, v32
	ds_write2st64_b32 v56, v37, v7 offset0:136 offset1:140
	v_lshlrev_b32_e32 v7, 16, v26
	ds_write2st64_b32 v56, v32, v7 offset0:168 offset1:172
	v_lshlrev_b32_e32 v7, 16, v27
	v_lshlrev_b32_e32 v21, 16, v21
	v_lshlrev_b32_e32 v11, 16, v35
	ds_write2st64_b32 v56, v7, v21 offset0:16 offset1:20
	v_lshlrev_b32_e32 v7, 16, v29
	v_mul_f32_e32 v11, 0xbfb8aa3b, v11
	v_mul_f32_e32 v7, 0xbfb8aa3b, v7
	v_exp_f32_e32 v11, v11
	v_exp_f32_e32 v7, v7
	v_lshlrev_b32_e32 v13, 16, v39
	v_lshlrev_b32_e32 v26, 16, v30
	v_lshlrev_b32_e32 v27, 16, v28
	ds_write2st64_b32 v56, v11, v7 offset0:48 offset1:52
	v_lshlrev_b32_e32 v7, 16, v31
	ds_write2st64_b32 v56, v13, v7 offset0:80 offset1:84
	v_lshlrev_b32_e32 v7, 16, v24
	ds_write2st64_b32 v56, v26, v7 offset0:112 offset1:116
	v_lshlrev_b32_e32 v7, 16, v22
	v_lshlrev_b32_e32 v20, 16, v20
	ds_write2st64_b32 v56, v27, v7 offset0:144 offset1:148
	v_lshlrev_b32_e32 v7, 16, v14
	ds_write2st64_b32 v56, v20, v7 offset0:176 offset1:180
	v_lshlrev_b32_e32 v7, 16, v15
	v_lshlrev_b32_e32 v9, 16, v9
	v_lshlrev_b32_e32 v11, 16, v23
	ds_write2st64_b32 v56, v7, v9 offset0:24 offset1:28
	v_lshlrev_b32_e32 v7, 16, v17
	v_mul_f32_e32 v11, 0xbfb8aa3b, v11
	v_mul_f32_e32 v7, 0xbfb8aa3b, v7
	v_exp_f32_e32 v11, v11
	v_exp_f32_e32 v7, v7
	v_lshlrev_b32_e32 v13, 16, v25
	v_lshlrev_b32_e32 v14, 16, v18
	v_lshlrev_b32_e32 v15, 16, v16
	ds_write2st64_b32 v56, v11, v7 offset0:56 offset1:60
	v_lshlrev_b32_e32 v7, 16, v19
	ds_write2st64_b32 v56, v13, v7 offset0:88 offset1:92
	v_lshlrev_b32_e32 v7, 16, v12
	v_lshlrev_b32_e32 v8, 16, v8
	ds_write2st64_b32 v56, v14, v7 offset0:120 offset1:124
	v_lshlrev_b32_e32 v7, 16, v10
	v_lshlrev_b32_e32 v6, 16, v6
	ds_write2st64_b32 v56, v15, v7 offset0:152 offset1:156
	ds_write2st64_b32 v56, v8, v6 offset0:184 offset1:188
	v_lshl_add_u64 v[6:7], s[62:63], 0, v[2:3]
	global_load_ushort v10, v[6:7], off
	global_load_ushort v11, v[6:7], off offset:1024
	global_load_ushort v12, v[6:7], off offset:2048
	v_lshl_add_u64 v[6:7], s[72:73], 0, v[2:3]
	global_load_ushort v13, v[6:7], off
	global_load_ushort v14, v[6:7], off offset:1024
	v_lshl_add_u64 v[6:7], v[4:5], 0, s[10:11]
	s_add_i32 s10, s18, 32
	s_ashr_i32 s11, s10, 31
	s_mul_hi_i32 s2, s10, 0xc00
	s_add_u32 s62, s16, s19
	s_addc_u32 s63, s17, s2
	s_lshl_b64 s[72:73], s[10:11], 12
	s_add_u32 s72, s12, s72
	global_load_ushort v15, v[6:7], off
	s_addc_u32 s73, s13, s73
	v_lshl_add_u64 v[6:7], s[62:63], 0, v[2:3]
	global_load_ushort v16, v[6:7], off
	global_load_ushort v17, v[6:7], off offset:1024
	global_load_ushort v18, v[6:7], off offset:2048
	v_lshl_add_u64 v[6:7], s[72:73], 0, v[2:3]
	s_lshl_b64 s[10:11], s[10:11], 11
	global_load_ushort v19, v[6:7], off
	global_load_ushort v20, v[6:7], off offset:1024
	v_lshl_add_u64 v[6:7], v[4:5], 0, s[10:11]
	s_add_i32 s10, s18, 36
	s_ashr_i32 s11, s10, 31
	s_add_i32 s19, s3, 0x1b000
	s_mul_hi_i32 s2, s10, 0xc00
	s_add_u32 s62, s16, s19
	s_addc_u32 s63, s17, s2
	s_lshl_b64 s[72:73], s[10:11], 12
	s_add_u32 s72, s12, s72
	global_load_ushort v21, v[6:7], off
	s_addc_u32 s73, s13, s73
	v_lshl_add_u64 v[6:7], s[62:63], 0, v[2:3]
	global_load_ushort v22, v[6:7], off
	global_load_ushort v23, v[6:7], off offset:1024
	global_load_ushort v24, v[6:7], off offset:2048
	v_lshl_add_u64 v[6:7], s[72:73], 0, v[2:3]
	s_lshl_b64 s[10:11], s[10:11], 11
	global_load_ushort v25, v[6:7], off
; __device__ __forceinline__ void rwkv_load_chunk(RwkvRegs& R, int n, int pw, int b, int col, const bf16_t* RKV, const bf16_t* LO, const bf16_t* Y) {
; #pragma unroll
;     for (int i = 0; i < 8; ++i) { const int tt = pw + 4 * i, m = b * T_ + 32 * n + tt; const bf16_t* zr = RKV + (size_t)m * RKV_LD; const bf16_t* lo = LO + (size_t)m * 2048;
;         R.vr[i] = zr[col]; R.vx[i] = zr[512 + col]; R.vv[i] = zr[1024 + col]; R.ve[i] = lo[col]; R.va[i] = lo[512 + col]; R.vk[i] = Y[(size_t)m * D_ + col]; }
; }
; __device__ __forceinline__ void rwkv_scan(const Ctx& c, const Params& p, int o, int nblk) {
;     ...
;             rwkv_load_chunk(R, 1, pw, b, col, RKV, LO, Y);
	global_load_ushort v26, v[6:7], off offset:1024
	v_lshl_add_u64 v[6:7], v[4:5], 0, s[10:11]
	s_add_i32 s10, s18, 40
	s_ashr_i32 s11, s10, 31
	s_add_i32 s19, s3, 0x1e000
	s_mul_hi_i32 s2, s10, 0xc00
	s_add_u32 s62, s16, s19
	s_addc_u32 s63, s17, s2
	s_lshl_b64 s[72:73], s[10:11], 12
	s_add_u32 s72, s12, s72
	global_load_ushort v27, v[6:7], off
	s_addc_u32 s73, s13, s73
	v_lshl_add_u64 v[6:7], s[62:63], 0, v[2:3]
	global_load_ushort v28, v[6:7], off
	global_load_ushort v29, v[6:7], off offset:1024
	global_load_ushort v30, v[6:7], off offset:2048
	v_lshl_add_u64 v[6:7], s[72:73], 0, v[2:3]
	s_lshl_b64 s[10:11], s[10:11], 11
	global_load_ushort v31, v[6:7], off
	global_load_ushort v32, v[6:7], off offset:1024
	v_lshl_add_u64 v[6:7], v[4:5], 0, s[10:11]
	s_add_i32 s10, s18, 44
	s_ashr_i32 s11, s10, 31
	s_add_i32 s19, s3, 0x21000
	s_mul_hi_i32 s2, s10, 0xc00
	s_add_u32 s62, s16, s19
	s_addc_u32 s63, s17, s2
	s_lshl_b64 s[72:73], s[10:11], 12
	s_add_u32 s72, s12, s72
	global_load_ushort v33, v[6:7], off
	s_addc_u32 s73, s13, s73
	v_lshl_add_u64 v[6:7], s[62:63], 0, v[2:3]
	global_load_ushort v34, v[6:7], off
	global_load_ushort v35, v[6:7], off offset:1024
	global_load_ushort v36, v[6:7], off offset:2048
	v_lshl_add_u64 v[6:7], s[72:73], 0, v[2:3]
	s_lshl_b64 s[10:11], s[10:11], 11
	global_load_ushort v37, v[6:7], off
	global_load_ushort v38, v[6:7], off offset:1024
	v_lshl_add_u64 v[6:7], v[4:5], 0, s[10:11]
	s_add_i32 s10, s18, 48
	s_ashr_i32 s11, s10, 31
	s_add_i32 s19, s3, 0x24000
	s_mul_hi_i32 s2, s10, 0xc00
	s_add_u32 s62, s16, s19
	s_addc_u32 s63, s17, s2
	s_lshl_b64 s[72:73], s[10:11], 12
	s_add_u32 s72, s12, s72
	global_load_ushort v39, v[6:7], off
	s_addc_u32 s73, s13, s73
	v_lshl_add_u64 v[6:7], s[62:63], 0, v[2:3]
	global_load_ushort v40, v[6:7], off
	global_load_ushort v41, v[6:7], off offset:1024
	global_load_ushort v42, v[6:7], off offset:2048
	v_lshl_add_u64 v[6:7], s[72:73], 0, v[2:3]
	s_lshl_b64 s[10:11], s[10:11], 11
	global_load_ushort v43, v[6:7], off
	global_load_ushort v44, v[6:7], off offset:1024
	v_lshl_add_u64 v[6:7], v[4:5], 0, s[10:11]
	s_add_i32 s10, s18, 52
	s_ashr_i32 s11, s10, 31
	s_add_i32 s19, s3, 0x27000
	s_mul_hi_i32 s2, s10, 0xc00
	s_add_u32 s62, s16, s19
	s_addc_u32 s63, s17, s2
	s_lshl_b64 s[72:73], s[10:11], 12
	s_add_u32 s72, s12, s72
	global_load_ushort v45, v[6:7], off
	s_addc_u32 s73, s13, s73
	v_lshl_add_u64 v[6:7], s[62:63], 0, v[2:3]
	global_load_ushort v46, v[6:7], off
	global_load_ushort v47, v[6:7], off offset:1024
	global_load_ushort v48, v[6:7], off offset:2048
	v_lshl_add_u64 v[6:7], s[72:73], 0, v[2:3]
	s_lshl_b64 s[10:11], s[10:11], 11
	global_load_ushort v49, v[6:7], off
	global_load_ushort v50, v[6:7], off offset:1024
	v_lshl_add_u64 v[6:7], v[4:5], 0, s[10:11]
	s_add_i32 s10, s18, 56
	s_ashr_i32 s11, s10, 31
	s_add_i32 s3, s3, 0x2a000
	s_mul_hi_i32 s18, s10, 0xc00
	s_add_u32 s2, s16, s3
	s_addc_u32 s3, s17, s18
	s_lshl_b64 s[18:19], s[10:11], 12
	s_add_u32 s18, s12, s18
	global_load_ushort v51, v[6:7], off
	s_addc_u32 s19, s13, s19
	v_lshl_add_u64 v[6:7], s[2:3], 0, v[2:3]
	global_load_ushort v52, v[6:7], off
	global_load_ushort v53, v[6:7], off offset:1024
	global_load_ushort v59, v[6:7], off offset:2048
	v_lshl_add_u64 v[6:7], s[18:19], 0, v[2:3]
	s_lshl_b64 s[2:3], s[10:11], 11
	global_load_ushort v60, v[6:7], off
	global_load_ushort v61, v[6:7], off offset:1024
	v_lshl_add_u64 v[6:7], v[4:5], 0, s[2:3]
	global_load_ushort v62, v[6:7], off
	v_lshl_add_u64 v[6:7], s[16:17], 0, v[2:3]
	v_lshl_add_u64 v[8:9], s[12:13], 0, v[2:3]
	s_waitcnt vmcnt(0)
	v_lshlrev_b32_e32 v10, 16, v10
	v_lshlrev_b32_e32 v11, 16, v11
	v_lshlrev_b32_e32 v12, 16, v12
	v_lshlrev_b32_e32 v13, 16, v13
	v_lshlrev_b32_e32 v14, 16, v14
	v_lshlrev_b32_e32 v15, 16, v15
	v_lshlrev_b32_e32 v16, 16, v16
	v_lshlrev_b32_e32 v17, 16, v17
	v_lshlrev_b32_e32 v18, 16, v18
	v_lshlrev_b32_e32 v19, 16, v19
	v_lshlrev_b32_e32 v20, 16, v20
	v_lshlrev_b32_e32 v21, 16, v21
	v_lshlrev_b32_e32 v22, 16, v22
	v_lshlrev_b32_e32 v23, 16, v23
	v_lshlrev_b32_e32 v24, 16, v24
	v_lshlrev_b32_e32 v25, 16, v25
	v_lshlrev_b32_e32 v26, 16, v26
	v_lshlrev_b32_e32 v27, 16, v27
	v_lshlrev_b32_e32 v28, 16, v28
	v_lshlrev_b32_e32 v29, 16, v29
	v_lshlrev_b32_e32 v30, 16, v30
	v_lshlrev_b32_e32 v31, 16, v31
	v_lshlrev_b32_e32 v32, 16, v32
	v_lshlrev_b32_e32 v33, 16, v33
	v_lshlrev_b32_e32 v34, 16, v34
	v_lshlrev_b32_e32 v35, 16, v35
	v_lshlrev_b32_e32 v36, 16, v36
	v_lshlrev_b32_e32 v37, 16, v37
	v_lshlrev_b32_e32 v38, 16, v38
	v_lshlrev_b32_e32 v39, 16, v39
	v_lshlrev_b32_e32 v40, 16, v40
	v_lshlrev_b32_e32 v41, 16, v41
	v_lshlrev_b32_e32 v42, 16, v42
	v_lshlrev_b32_e32 v43, 16, v43
	v_lshlrev_b32_e32 v44, 16, v44
	v_lshlrev_b32_e32 v45, 16, v45
	v_lshlrev_b32_e32 v46, 16, v46
	v_lshlrev_b32_e32 v47, 16, v47
	v_lshlrev_b32_e32 v48, 16, v48
	v_lshlrev_b32_e32 v49, 16, v49
	v_lshlrev_b32_e32 v50, 16, v50
	v_lshlrev_b32_e32 v51, 16, v51
	v_lshlrev_b32_e32 v52, 16, v52
	v_lshlrev_b32_e32 v53, 16, v53
	v_lshlrev_b32_e32 v59, 16, v59
	v_lshlrev_b32_e32 v60, 16, v60
	v_lshlrev_b32_e32 v61, 16, v61
	v_lshlrev_b32_e32 v62, 16, v62
	s_mov_b32 s72, 0
	s_mov_b32 s2, 0
	s_branch .LBB0_99

; #define LAS __attribute__((address_space(3)))
; __device__ __forceinline__ float bf2f(bf16_t b) { return asf((unsigned)b << 16); }
; __device__ __forceinline__ void rwkv_load_chunk(RwkvRegs& R, int n, int pw, int b, int col, const bf16_t* RKV, const bf16_t* LO, const bf16_t* Y) {
; #pragma unroll
;     for (int i = 0; i < 8; ++i) { const int tt = pw + 4 * i, m = b * T_ + 32 * n + tt; const bf16_t* zr = RKV + (size_t)m * RKV_LD; const bf16_t* lo = LO + (size_t)m * 2048;
;         R.vr[i] = zr[col]; R.vx[i] = zr[512 + col]; R.vv[i] = zr[1024 + col]; R.ve[i] = lo[col]; R.va[i] = lo[512 + col]; R.vk[i] = Y[(size_t)m * D_ + col]; }
; }
; __device__ __forceinline__ void rwkv_write_chunk(LAS float* L, const RwkvRegs& R, int n, int pw, int lane) {
;     LAS float* st = L + (n & 1) * 12288;
; #pragma unroll
;     for (int i = 0; i < 8; ++i) { const int tt = pw + 4 * i; LAS float* q = st + tt * 64 + lane;
;         q[0] = bf2f(R.vr[i]); q[2048] = __expf(-bf2f(R.ve[i])); q[4096] = bf2f(R.vx[i]); q[6144] = bf2f(R.vk[i]); q[8192] = bf2f(R.va[i]); q[10240] = bf2f(R.vv[i]); }
; }
.LBB0_99:
	s_waitcnt lgkmcnt(0)
	s_barrier
	s_add_i32 s10, s2, 1
	s_cmpk_eq_i32 s72, 0x1fe0
	s_cbranch_scc1 .LBB0_101
	s_bitcmp1_b32 s10, 0
	s_cselect_b32 s3, 0xc000, 0
	v_add_u32_e32 v63, s3, v56
	s_waitcnt vmcnt(0) lgkmcnt(0)
	v_mul_f32_e32 v64, 0xbfb8aa3b, v13
	v_mul_f32_e32 v65, 0xbfb8aa3b, v19
	v_exp_f32_e32 v64, v64
	v_exp_f32_e32 v65, v65
	ds_write2st64_b32 v63, v10, v16 offset1:4
	ds_write2st64_b32 v63, v11, v17 offset0:64 offset1:68
	ds_write2st64_b32 v63, v64, v65 offset0:32 offset1:36
	ds_write2st64_b32 v63, v15, v21 offset0:96 offset1:100
	ds_write2st64_b32 v63, v14, v20 offset0:128 offset1:132
	ds_write2st64_b32 v63, v12, v18 offset0:160 offset1:164
	v_mul_f32_e32 v64, 0xbfb8aa3b, v25
	v_mul_f32_e32 v65, 0xbfb8aa3b, v31
	v_exp_f32_e32 v64, v64
	v_exp_f32_e32 v65, v65
	ds_write2st64_b32 v63, v22, v28 offset0:8 offset1:12
	ds_write2st64_b32 v63, v23, v29 offset0:72 offset1:76
	ds_write2st64_b32 v63, v64, v65 offset0:40 offset1:44
	ds_write2st64_b32 v63, v27, v33 offset0:104 offset1:108
	ds_write2st64_b32 v63, v26, v32 offset0:136 offset1:140
	ds_write2st64_b32 v63, v24, v30 offset0:168 offset1:172
	v_mul_f32_e32 v64, 0xbfb8aa3b, v37
	v_mul_f32_e32 v65, 0xbfb8aa3b, v43
	v_exp_f32_e32 v64, v64
	v_exp_f32_e32 v65, v65
	ds_write2st64_b32 v63, v34, v40 offset0:16 offset1:20
	ds_write2st64_b32 v63, v35, v41 offset0:80 offset1:84
	ds_write2st64_b32 v63, v64, v65 offset0:48 offset1:52
	ds_write2st64_b32 v63, v39, v45 offset0:112 offset1:116
	ds_write2st64_b32 v63, v38, v44 offset0:144 offset1:148
	ds_write2st64_b32 v63, v36, v42 offset0:176 offset1:180
	v_mul_f32_e32 v64, 0xbfb8aa3b, v49
	v_mul_f32_e32 v65, 0xbfb8aa3b, v60
	v_exp_f32_e32 v64, v64
	v_exp_f32_e32 v65, v65
	ds_write2st64_b32 v63, v46, v52 offset0:24 offset1:28
	ds_write2st64_b32 v63, v47, v53 offset0:88 offset1:92
	ds_write2st64_b32 v63, v64, v65 offset0:56 offset1:60
	ds_write2st64_b32 v63, v51, v62 offset0:120 offset1:124
	ds_write2st64_b32 v63, v50, v61 offset0:152 offset1:156
	ds_write2st64_b32 v63, v48, v59 offset0:184 offset1:188
.LBB0_101:
	s_cmpk_gt_u32 s2, 0xfd
	s_cbranch_scc1 .LBB0_103
	s_add_i32 s11, s59, s72
	s_add_i32 s2, s11, 60
	s_mul_i32 s18, s2, 0xc00
	s_add_u32 s18, s16, s18
	s_addc_u32 s19, s17, 0
	s_lshl_b32 s62, s2, 12
	s_add_u32 s62, s12, s62
	s_addc_u32 s63, s13, 0
	s_lshl_b32 s2, s2, 11
	s_add_u32 s2, s74, s2
	s_addc_u32 s3, s75, 0
	s_waitcnt lgkmcnt(0)
	global_load_short_d16_hi v10, v2, s[18:19]
	global_load_short_d16_hi v11, v2, s[18:19] offset:1024
	global_load_short_d16_hi v12, v2, s[18:19] offset:2048
	global_load_short_d16_hi v13, v2, s[62:63]
	global_load_short_d16_hi v14, v2, s[62:63] offset:1024
	global_load_short_d16_hi v15, v2, s[2:3]
	s_add_u32 s18, s18, 0x3000
	s_addc_u32 s19, s19, 0
	s_add_u32 s62, s62, 0x4000
	s_addc_u32 s63, s63, 0
	s_add_u32 s2, s2, 0x2000
	s_addc_u32 s3, s3, 0
	global_load_short_d16_hi v16, v2, s[18:19]
	global_load_short_d16_hi v17, v2, s[18:19] offset:1024
	global_load_short_d16_hi v18, v2, s[18:19] offset:2048
	global_load_short_d16_hi v19, v2, s[62:63]
	global_load_short_d16_hi v20, v2, s[62:63] offset:1024
	global_load_short_d16_hi v21, v2, s[2:3]
	s_add_u32 s18, s18, 0x3000
	s_addc_u32 s19, s19, 0
	s_add_u32 s62, s62, 0x4000
	s_addc_u32 s63, s63, 0
	s_add_u32 s2, s2, 0x2000
	s_addc_u32 s3, s3, 0
	global_load_short_d16_hi v22, v2, s[18:19]
	global_load_short_d16_hi v23, v2, s[18:19] offset:1024
	global_load_short_d16_hi v24, v2, s[18:19] offset:2048
	global_load_short_d16_hi v25, v2, s[62:63]
	global_load_short_d16_hi v26, v2, s[62:63] offset:1024
	global_load_short_d16_hi v27, v2, s[2:3]
	s_add_u32 s18, s18, 0x3000
	s_addc_u32 s19, s19, 0
	s_add_u32 s62, s62, 0x4000
	s_addc_u32 s63, s63, 0
	s_add_u32 s2, s2, 0x2000
	s_addc_u32 s3, s3, 0
	global_load_short_d16_hi v28, v2, s[18:19]
	global_load_short_d16_hi v29, v2, s[18:19] offset:1024
	global_load_short_d16_hi v30, v2, s[18:19] offset:2048
	global_load_short_d16_hi v31, v2, s[62:63]
	global_load_short_d16_hi v32, v2, s[62:63] offset:1024
	global_load_short_d16_hi v33, v2, s[2:3]
	s_add_u32 s18, s18, 0x3000
	s_addc_u32 s19, s19, 0
	s_add_u32 s62, s62, 0x4000
	s_addc_u32 s63, s63, 0
	s_add_u32 s2, s2, 0x2000
	s_addc_u32 s3, s3, 0
	global_load_short_d16_hi v34, v2, s[18:19]
	global_load_short_d16_hi v35, v2, s[18:19] offset:1024
	global_load_short_d16_hi v36, v2, s[18:19] offset:2048
	global_load_short_d16_hi v37, v2, s[62:63]
	global_load_short_d16_hi v38, v2, s[62:63] offset:1024
	global_load_short_d16_hi v39, v2, s[2:3]
	s_add_u32 s18, s18, 0x3000
	s_addc_u32 s19, s19, 0
	s_add_u32 s62, s62, 0x4000
	s_addc_u32 s63, s63, 0
	s_add_u32 s2, s2, 0x2000
	s_addc_u32 s3, s3, 0
	global_load_short_d16_hi v40, v2, s[18:19]
	global_load_short_d16_hi v41, v2, s[18:19] offset:1024
	global_load_short_d16_hi v42, v2, s[18:19] offset:2048
	global_load_short_d16_hi v43, v2, s[62:63]
	global_load_short_d16_hi v44, v2, s[62:63] offset:1024
	global_load_short_d16_hi v45, v2, s[2:3]
	s_add_u32 s18, s18, 0x3000
	s_addc_u32 s19, s19, 0
	s_add_u32 s62, s62, 0x4000
	s_addc_u32 s63, s63, 0
	s_add_u32 s2, s2, 0x2000
	s_addc_u32 s3, s3, 0
	global_load_short_d16_hi v46, v2, s[18:19]
	global_load_short_d16_hi v47, v2, s[18:19] offset:1024
	global_load_short_d16_hi v48, v2, s[18:19] offset:2048
	global_load_short_d16_hi v49, v2, s[62:63]
	global_load_short_d16_hi v50, v2, s[62:63] offset:1024
	global_load_short_d16_hi v51, v2, s[2:3]
	s_add_u32 s18, s18, 0x3000
	s_addc_u32 s19, s19, 0
	s_add_u32 s62, s62, 0x4000
	s_addc_u32 s63, s63, 0
	s_add_u32 s2, s2, 0x2000
	s_addc_u32 s3, s3, 0
	global_load_short_d16_hi v52, v2, s[18:19]
	global_load_short_d16_hi v53, v2, s[18:19] offset:1024
	global_load_short_d16_hi v59, v2, s[18:19] offset:2048
	global_load_short_d16_hi v60, v2, s[62:63]
	global_load_short_d16_hi v61, v2, s[62:63] offset:1024
	global_load_short_d16_hi v62, v2, s[2:3]
